# FFN-up last conv iteration: compiler-vectorised conv groups re-emitted as DPP fmac chains, dead shuffles removed
# speedup vs baseline: 1.0080x; 1.0080x over previous
; #define PG8_LAS __attribute__((address_space(3)))
;     __device__ __forceinline__ void operator()(f32x4 (&acc)[2][2][4][2], const Unit& u, int ui, int wr, int wc, int fr_, int fq_) const {
;     ...
;         for (int bj = 0; bj < 2; ++bj)
; #pragma unroll
;             for (int n = 0; n < 2; ++n) { const int ch = bj * 2816 + fbase + 4 * n;
;                 const f32x4 w0 = *(const f32x4*)(cw + ch), w1 = *(const f32x4*)(cw + 5632 + ch), w2 = *(const f32x4*)(cw + 2 * 5632 + ch), bb = *(const f32x4*)(cb + ch);
; #pragma unroll
;                 for (int ai = 0; ai < 2; ++ai) { const int kb = 2 * ai + wr;
;                     f32x4 c62 = (f32x4){0.f, 0.f, 0.f, 0.f}, c63 = c62;
;                     if (kb > 0) { c62 = *(const PG8_LAS f32x4*)(exch + (((kb - 1) * 2 + 0) * 256 + bj * HALF + 32 * wc + 8 * fq + 4 * n)); c63 = *(const PG8_LAS f32x4*)(exch + (((kb - 1) * 2 + 1) * 256 + bj * HALF + 32 * wc + 8 * fq + 4 * n)); }
; #pragma unroll
;                     for (int m = 3; m >= 0; --m) { f32x4 cur = acc[ai][bj][m][n], res;
; #pragma unroll
;                         for (int j = 0; j < 4; ++j) { const float c = cur[j]; const float pv = (m > 0) ? acc[ai][bj][m > 0 ? m - 1 : 0][n][j] : (fr == 15 ? c63[j] : c62[j]); float t1, t2;
;                             asm volatile("s_nop 1\n\tv_mov_b32_dpp %0, %3 row_ror:1 row_mask:0xf bank_mask:0xf\n\tv_mov_b32_dpp %1, %3 row_ror:2 row_mask:0xf bank_mask:0xf\n\t"
;                                          "v_mov_b32_dpp %0, %2 row_shr:1 row_mask:0xf bank_mask:0xf\n\tv_mov_b32_dpp %1, %2 row_shr:2 row_mask:0xf bank_mask:0xf"
;                                          : "=&v"(t1), "=&v"(t2) : "v"(c), "v"(pv));
;                             res[j] = bb[j] + w0[j] * t2 + w1[j] * t1 + w2[j] * c; }
;                         asm volatile("" : "+v"(res[0]), "+v"(res[1]), "+v"(res[2]), "+v"(res[3]));
;                         acc[ai][bj][m][n] = res; } }
.LBB0_1200:
	v_pk_mul_f32 v[76:77], v[6:7], v[190:191]
	v_pk_mul_f32 v[72:73], v[10:11], v[192:193]
	v_pk_mul_f32 v[4:5], v[4:5], v[188:189] op_sel_hi:[1,0]
	v_pk_mul_f32 v[2:3], v[2:3], v[188:189]
	v_pk_mul_f32 v[74:75], v[8:9], v[190:191] op_sel_hi:[1,0]
	v_mov_b32_e32 v7, v38
	v_fmac_f32_dpp v7, v50, v26 row_shr:2 row_mask:0xf bank_mask:0xf
	v_fmac_f32_dpp v7, v2, v26 row_shl:14 row_mask:0xf bank_mask:0xf
	v_fmac_f32_dpp v7, v50, v22 row_shr:1 row_mask:0xf bank_mask:0xf
	v_fmac_f32_dpp v7, v2, v22 row_shl:15 row_mask:0xf bank_mask:0xf
	v_fmac_f32_e32 v7, v50, v34
	v_mov_b32_e32 v6, v39
	v_fmac_f32_dpp v6, v51, v27 row_shr:2 row_mask:0xf bank_mask:0xf
	v_fmac_f32_dpp v6, v3, v27 row_shl:14 row_mask:0xf bank_mask:0xf
	v_fmac_f32_dpp v6, v51, v23 row_shr:1 row_mask:0xf bank_mask:0xf
	v_fmac_f32_dpp v6, v3, v23 row_shl:15 row_mask:0xf bank_mask:0xf
	v_fmac_f32_e32 v6, v51, v35
	v_mov_b32_e32 v46, v192
	v_mov_b32_e32 v47, v192
	v_pk_mul_f32 v[64:65], v[12:13], v[46:47]
	v_mov_b32_e32 v8, v40
	v_fmac_f32_dpp v8, v52, v28 row_shr:2 row_mask:0xf bank_mask:0xf
	v_fmac_f32_dpp v8, v4, v28 row_shl:14 row_mask:0xf bank_mask:0xf
	v_fmac_f32_dpp v8, v52, v24 row_shr:1 row_mask:0xf bank_mask:0xf
	v_fmac_f32_dpp v8, v4, v24 row_shl:15 row_mask:0xf bank_mask:0xf
	v_fmac_f32_e32 v8, v52, v36
	v_mov_b32_e32 v9, v41
	v_fmac_f32_dpp v9, v53, v29 row_shr:2 row_mask:0xf bank_mask:0xf
	v_fmac_f32_dpp v9, v5, v29 row_shl:14 row_mask:0xf bank_mask:0xf
	v_fmac_f32_dpp v9, v53, v25 row_shr:1 row_mask:0xf bank_mask:0xf
	v_fmac_f32_dpp v9, v5, v25 row_shl:15 row_mask:0xf bank_mask:0xf
	v_fmac_f32_e32 v9, v53, v37
	v_mov_b32_e32 v11, v38
	v_fmac_f32_dpp v11, v2, v26 row_shr:2 row_mask:0xf bank_mask:0xf
	v_fmac_f32_dpp v11, v76, v26 row_shl:14 row_mask:0xf bank_mask:0xf
	v_fmac_f32_dpp v11, v2, v22 row_shr:1 row_mask:0xf bank_mask:0xf
	v_fmac_f32_dpp v11, v76, v22 row_shl:15 row_mask:0xf bank_mask:0xf
	v_fmac_f32_e32 v11, v2, v34
	s_waitcnt lgkmcnt(0)
	v_cndmask_b32_e64 v17, v45, v17, s[8:9]
	v_mov_b32_e32 v2, v3
	v_mov_b32_e32 v10, v39
	s_nop 0
	v_fmac_f32_dpp v10, v2, v27 row_shr:2 row_mask:0xf bank_mask:0xf
	v_fmac_f32_dpp v10, v77, v27 row_shl:14 row_mask:0xf bank_mask:0xf
	v_fmac_f32_dpp v10, v2, v23 row_shr:1 row_mask:0xf bank_mask:0xf
	v_fmac_f32_dpp v10, v77, v23 row_shl:15 row_mask:0xf bank_mask:0xf
	v_fmac_f32_e32 v10, v2, v35
	v_mov_b32_e32 v12, v40
	v_fmac_f32_dpp v12, v4, v28 row_shr:2 row_mask:0xf bank_mask:0xf
	v_fmac_f32_dpp v12, v74, v28 row_shl:14 row_mask:0xf bank_mask:0xf
	v_fmac_f32_dpp v12, v4, v24 row_shr:1 row_mask:0xf bank_mask:0xf
	v_fmac_f32_dpp v12, v74, v24 row_shl:15 row_mask:0xf bank_mask:0xf
	v_fmac_f32_e32 v12, v4, v36
	v_mov_b32_e32 v4, v5
	v_mov_b32_e32 v13, v41
	s_nop 0
	v_fmac_f32_dpp v13, v4, v29 row_shr:2 row_mask:0xf bank_mask:0xf
	v_fmac_f32_dpp v13, v75, v29 row_shl:14 row_mask:0xf bank_mask:0xf
	v_fmac_f32_dpp v13, v4, v25 row_shr:1 row_mask:0xf bank_mask:0xf
	v_fmac_f32_dpp v13, v75, v25 row_shl:15 row_mask:0xf bank_mask:0xf
	v_fmac_f32_e32 v13, v4, v37
	v_mov_b32_e32 v47, v38
	v_fmac_f32_dpp v47, v76, v26 row_shr:2 row_mask:0xf bank_mask:0xf
	v_fmac_f32_dpp v47, v72, v26 row_shl:14 row_mask:0xf bank_mask:0xf
	v_fmac_f32_dpp v47, v76, v22 row_shr:1 row_mask:0xf bank_mask:0xf
	v_fmac_f32_dpp v47, v72, v22 row_shl:15 row_mask:0xf bank_mask:0xf
	v_fmac_f32_e32 v47, v76, v34
	v_mov_b32_e32 v46, v39
	v_fmac_f32_dpp v46, v77, v27 row_shr:2 row_mask:0xf bank_mask:0xf
	v_fmac_f32_dpp v46, v73, v27 row_shl:14 row_mask:0xf bank_mask:0xf
	v_fmac_f32_dpp v46, v77, v23 row_shr:1 row_mask:0xf bank_mask:0xf
	v_fmac_f32_dpp v46, v73, v23 row_shl:15 row_mask:0xf bank_mask:0xf
	v_fmac_f32_e32 v46, v77, v35
	v_mov_b32_e32 v50, v40
	v_fmac_f32_dpp v50, v74, v28 row_shr:2 row_mask:0xf bank_mask:0xf
	v_fmac_f32_dpp v50, v64, v28 row_shl:14 row_mask:0xf bank_mask:0xf
	v_fmac_f32_dpp v50, v74, v24 row_shr:1 row_mask:0xf bank_mask:0xf
	v_fmac_f32_dpp v50, v64, v24 row_shl:15 row_mask:0xf bank_mask:0xf
	v_fmac_f32_e32 v50, v74, v36
	v_mov_b32_e32 v51, v41
	v_fmac_f32_dpp v51, v75, v29 row_shr:2 row_mask:0xf bank_mask:0xf
	v_fmac_f32_dpp v51, v65, v29 row_shl:14 row_mask:0xf bank_mask:0xf
	v_fmac_f32_dpp v51, v75, v25 row_shr:1 row_mask:0xf bank_mask:0xf
	v_fmac_f32_dpp v51, v65, v25 row_shl:15 row_mask:0xf bank_mask:0xf
	v_fmac_f32_e32 v51, v75, v37
	v_cndmask_b32_e64 v4, v43, v15, s[8:9]
	v_cndmask_b32_e64 v3, v42, v14, s[8:9]
	v_cndmask_b32_e64 v2, v44, v16, s[8:9]
	v_mov_b32_e32 v252, v38
	v_fmac_f32_dpp v252, v72, v26 row_shr:2 row_mask:0xf bank_mask:0xf
	v_fmac_f32_dpp v252, v3, v26 row_shl:14 row_mask:0xf bank_mask:0xf
	v_fmac_f32_dpp v252, v72, v22 row_shr:1 row_mask:0xf bank_mask:0xf
	v_fmac_f32_dpp v252, v3, v22 row_shl:15 row_mask:0xf bank_mask:0xf
	v_fmac_f32_e32 v252, v72, v34
	v_mov_b32_e32 v231, v39
	v_fmac_f32_dpp v231, v73, v27 row_shr:2 row_mask:0xf bank_mask:0xf
	v_fmac_f32_dpp v231, v4, v27 row_shl:14 row_mask:0xf bank_mask:0xf
	v_fmac_f32_dpp v231, v73, v23 row_shr:1 row_mask:0xf bank_mask:0xf
	v_fmac_f32_dpp v231, v4, v23 row_shl:15 row_mask:0xf bank_mask:0xf
	v_fmac_f32_e32 v231, v73, v35
	v_mov_b32_e32 v15, v40
	v_fmac_f32_dpp v15, v64, v28 row_shr:2 row_mask:0xf bank_mask:0xf
	v_fmac_f32_dpp v15, v2, v28 row_shl:14 row_mask:0xf bank_mask:0xf
	v_fmac_f32_dpp v15, v64, v24 row_shr:1 row_mask:0xf bank_mask:0xf
	v_fmac_f32_dpp v15, v2, v24 row_shl:15 row_mask:0xf bank_mask:0xf
	v_fmac_f32_e32 v15, v64, v36
	v_mov_b32_e32 v27, v231
	v_mov_b32_e32 v26, v252
	v_mov_b32_e32 v28, v41
	v_fmac_f32_dpp v28, v65, v29 row_shr:2 row_mask:0xf bank_mask:0xf
	v_fmac_f32_dpp v28, v17, v29 row_shl:14 row_mask:0xf bank_mask:0xf
; __device__ __forceinline__ unsigned cvt_pk_bf16(float lo, float hi) { unsigned r; asm volatile("v_cvt_pk_bf16_f32 %0, %1, %2" : "=v"(r) : "v"(lo), "v"(hi)); return r; }
;     __device__ __forceinline__ void operator()(f32x4 (&acc)[2][2][4][2], const Unit& u, int ui, int wr, int wc, int fr_, int fq_) const {
;     ...
;                     for (int m = 3; m >= 0; --m) { f32x4 cur = acc[ai][bj][m][n], res;
; #pragma unroll
;                         for (int j = 0; j < 4; ++j) { const float c = cur[j]; const float pv = (m > 0) ? acc[ai][bj][m > 0 ? m - 1 : 0][n][j] : (fr == 15 ? c63[j] : c62[j]); float t1, t2;
;                             asm volatile("s_nop 1\n\tv_mov_b32_dpp %0, %3 row_ror:1 row_mask:0xf bank_mask:0xf\n\tv_mov_b32_dpp %1, %3 row_ror:2 row_mask:0xf bank_mask:0xf\n\t"
;                                          "v_mov_b32_dpp %0, %2 row_shr:1 row_mask:0xf bank_mask:0xf\n\tv_mov_b32_dpp %1, %2 row_shr:2 row_mask:0xf bank_mask:0xf"
;                                          : "=&v"(t1), "=&v"(t2) : "v"(c), "v"(pv));
;                             res[j] = bb[j] + w0[j] * t2 + w1[j] * t1 + w2[j] * c; }
;                         asm volatile("" : "+v"(res[0]), "+v"(res[1]), "+v"(res[2]), "+v"(res[3]));
;                         acc[ai][bj][m][n] = res; } }
;                 asm volatile("" ::: "memory"); }
;         const int row0 = u.pm * BM + wr * 64 + fr;
; #pragma unroll
;         for (int ai = 0; ai < 2; ++ai)
; #pragma unroll
;             for (int m = 0; m < 4; ++m) { float gv[8];
; #pragma unroll
;                 for (int n = 0; n < 2; ++n)
; #pragma unroll
;                     for (int j = 0; j < 4; ++j) { const float g = acc[ai][0][m][n][j], up = acc[ai][1][m][n][j]; gv[n * 4 + j] = g * __builtin_amdgcn_rcpf(1.0f + __builtin_amdgcn_exp2f(g * -1.4426950408889634f)) * up; }
;                 u32x4 w; w.x = cvt_pk_bf16(gv[0], gv[1]); w.y = cvt_pk_bf16(gv[2], gv[3]); w.z = cvt_pk_bf16(gv[4], gv[5]); w.w = cvt_pk_bf16(gv[6], gv[7]);
;                 *(u32x4*)(G + (size_t)(row0 + ai * HALF + m * 16) * 2816 + fbase) = w; asm volatile("" ::: "memory"); }
	v_fmac_f32_dpp v28, v65, v25 row_shr:1 row_mask:0xf bank_mask:0xf
	v_fmac_f32_dpp v28, v17, v25 row_shl:15 row_mask:0xf bank_mask:0xf
	v_fmac_f32_e32 v28, v65, v37
	v_mul_f32_e32 v22, s98, v123
	v_mul_f32_e32 v2, s98, v223
	v_mul_f32_e32 v3, s98, v224
	v_exp_f32_e32 v2, v2
	v_exp_f32_e32 v3, v3
	v_mul_f32_e32 v4, s98, v221
	v_mul_f32_e32 v5, s98, v222
	v_mul_f32_e32 v16, s98, v126
	v_mul_f32_e32 v17, s98, v122
	v_exp_f32_e32 v22, v22
	v_mul_f32_e32 v23, s98, v124
	v_exp_f32_e32 v4, v4
	v_exp_f32_e32 v5, v5
	v_exp_f32_e32 v16, v16
	v_exp_f32_e32 v17, v17
	v_exp_f32_e32 v23, v23
	v_add_f32_e32 v2, 1.0, v2
	v_add_f32_e32 v3, 1.0, v3
	v_add_f32_e32 v22, 1.0, v22
	v_rcp_f32_e32 v2, v2
	v_rcp_f32_e32 v3, v3
	v_add_f32_e32 v4, 1.0, v4
	v_add_f32_e32 v5, 1.0, v5
	v_add_f32_e32 v16, 1.0, v16
	v_add_f32_e32 v17, 1.0, v17
	v_rcp_f32_e32 v22, v22
	v_add_f32_e32 v23, 1.0, v23
	v_rcp_f32_e32 v4, v4
	v_rcp_f32_e32 v5, v5
	v_rcp_f32_e32 v16, v16
	v_rcp_f32_e32 v17, v17
	v_rcp_f32_e32 v23, v23
	s_lshl_b32 s0, s76, 8
	v_mul_f32_e32 v2, v223, v2
	v_mul_f32_e32 v3, v224, v3
	v_mul_f32_e32 v22, v123, v22
	s_add_i32 s0, s0, s68
	v_mul_f32_e32 v2, v2, v97
	v_mul_f32_e32 v3, v3, v96
	v_mul_f32_e32 v4, v221, v4
	v_mul_f32_e32 v5, v222, v5
	v_mul_f32_e32 v16, v126, v16
	v_mul_f32_e32 v17, v122, v17
	v_mul_f32_e32 v25, v22, v59
	v_mul_f32_e32 v22, v124, v23
	v_add_u32_e32 v14, s0, v210
	v_mul_f32_e32 v4, v4, v95
	v_mul_f32_e32 v5, v5, v94
	v_mul_f32_e32 v16, v16, v62
	v_mul_f32_e32 v17, v17, v58
	v_mul_f32_e32 v29, v22, v60
	v_cvt_pk_bf16_f32 v22, v2, v3
	v_mov_b64_e32 v[2:3], s[38:39]
	v_cvt_pk_bf16_f32 v23, v4, v5
	v_cvt_pk_bf16_f32 v24, v16, v17
	v_mad_i64_i32 v[16:17], s[0:1], v14, s83, v[2:3]
	v_lshlrev_b64 v[4:5], 1, v[186:187]
	v_lshl_add_u64 v[16:17], v[16:17], 0, v[4:5]
	v_cvt_pk_bf16_f32 v25, v25, v29
	global_store_dwordx4 v[16:17], v[22:25], off
	v_mul_f32_e32 v29, s98, v218
	v_exp_f32_e32 v29, v29
	v_mul_f32_e32 v22, s98, v217
	v_exp_f32_e32 v22, v22
	v_mul_f32_e32 v23, s98, v219
	v_exp_f32_e32 v23, v23
	v_mul_f32_e32 v24, s98, v225
	v_add_f32_e32 v22, 1.0, v22
	v_rcp_f32_e32 v22, v22
	v_add_f32_e32 v23, 1.0, v23
	v_rcp_f32_e32 v23, v23
	v_exp_f32_e32 v24, v24
	v_mul_f32_e32 v22, v217, v22
	v_mul_f32_e32 v25, v22, v108
	v_mul_f32_e32 v22, v219, v23
	v_add_f32_e32 v23, 1.0, v24
	v_mul_f32_e32 v34, s98, v220
	v_rcp_f32_e32 v23, v23
	v_mul_f32_e32 v24, s98, v144
	v_exp_f32_e32 v34, v34
	v_exp_f32_e32 v24, v24
	v_add_f32_e32 v16, 1.0, v29
	v_mul_f32_e32 v29, v22, v109
	v_mul_f32_e32 v22, v225, v23
	v_mul_f32_e32 v23, s98, v145
	v_add_f32_e32 v17, 1.0, v34
	v_mul_f32_e32 v34, v22, v69
	v_add_f32_e32 v22, 1.0, v24
	v_exp_f32_e32 v23, v23
	v_mul_f32_e32 v24, s98, v226
	v_exp_f32_e32 v24, v24
	v_rcp_f32_e32 v22, v22
	v_add_f32_e32 v23, 1.0, v23
	v_rcp_f32_e32 v16, v16
	v_rcp_f32_e32 v23, v23
	v_add_f32_e32 v24, 1.0, v24
	v_rcp_f32_e32 v17, v17
	v_rcp_f32_e32 v24, v24
	v_mul_f32_e32 v22, v144, v22
	v_mul_f32_e32 v16, v218, v16
	v_mul_f32_e32 v35, v22, v67
	v_mul_f32_e32 v22, v145, v23
	v_mul_f32_e32 v16, v16, v127
	v_mul_f32_e32 v17, v220, v17
	v_mul_f32_e32 v36, v22, v68
	v_mul_f32_e32 v22, v226, v24
	v_mul_f32_e32 v17, v17, v125
	v_mul_f32_e32 v37, v22, v70
	v_cvt_pk_bf16_f32 v22, v16, v17
	v_add_u32_e32 v16, 16, v14
	v_mad_i64_i32 v[16:17], s[0:1], v16, s83, v[2:3]
	v_lshl_add_u64 v[16:17], v[16:17], 0, v[4:5]
	v_cvt_pk_bf16_f32 v23, v25, v29
	v_cvt_pk_bf16_f32 v24, v34, v35
	v_cvt_pk_bf16_f32 v25, v36, v37
	global_store_dwordx4 v[16:17], v[22:25], off
	v_mul_f32_e32 v29, s98, v213
	v_exp_f32_e32 v29, v29
	v_mul_f32_e32 v22, s98, v154
	v_exp_f32_e32 v22, v22
	v_mul_f32_e32 v23, s98, v214
	v_exp_f32_e32 v23, v23
	v_mul_f32_e32 v24, s98, v142
	v_add_f32_e32 v22, 1.0, v22
	v_rcp_f32_e32 v22, v22
	v_add_f32_e32 v23, 1.0, v23
	v_rcp_f32_e32 v23, v23
	v_exp_f32_e32 v24, v24
	v_mul_f32_e32 v22, v154, v22
	v_mul_f32_e32 v25, v22, v100
	v_mul_f32_e32 v22, v214, v23
	v_add_f32_e32 v23, 1.0, v24
	v_mul_f32_e32 v34, s98, v216
	v_rcp_f32_e32 v23, v23
	v_mul_f32_e32 v24, s98, v136
	v_exp_f32_e32 v34, v34
	v_exp_f32_e32 v24, v24
	v_add_f32_e32 v16, 1.0, v29
	v_mul_f32_e32 v29, v22, v101
	v_mul_f32_e32 v22, v142, v23
	v_mul_f32_e32 v23, s98, v137
	v_add_f32_e32 v17, 1.0, v34
	v_mul_f32_e32 v34, v22, v56
	v_add_f32_e32 v22, 1.0, v24
	v_exp_f32_e32 v23, v23
	v_mul_f32_e32 v24, s98, v143
	v_exp_f32_e32 v24, v24
	v_rcp_f32_e32 v22, v22
	v_add_f32_e32 v23, 1.0, v23
	v_rcp_f32_e32 v16, v16
	v_rcp_f32_e32 v23, v23
	v_add_f32_e32 v24, 1.0, v24
	v_rcp_f32_e32 v17, v17
	v_rcp_f32_e32 v24, v24
	v_mul_f32_e32 v22, v136, v22
	v_mul_f32_e32 v16, v213, v16
	v_mul_f32_e32 v30, v22, v30
	v_mul_f32_e32 v22, v137, v23
	v_mul_f32_e32 v16, v16, v107
	v_mul_f32_e32 v17, v216, v17
	v_mul_f32_e32 v31, v22, v31
	v_mul_f32_e32 v22, v143, v24
	v_mul_f32_e32 v17, v17, v105
	v_mul_f32_e32 v35, v22, v66
	v_cvt_pk_bf16_f32 v22, v16, v17
	v_add_u32_e32 v16, 32, v14
	v_mad_i64_i32 v[16:17], s[0:1], v16, s83, v[2:3]
	v_cvt_pk_bf16_f32 v23, v25, v29
	v_cvt_pk_bf16_f32 v24, v34, v30
	v_lshl_add_u64 v[16:17], v[16:17], 0, v[4:5]
	v_cvt_pk_bf16_f32 v25, v31, v35
	global_store_dwordx4 v[16:17], v[22:25], off
	v_mul_f32_e32 v29, s98, v211
	v_exp_f32_e32 v29, v29
	v_mul_f32_e32 v24, s98, v133
	v_exp_f32_e32 v24, v24
	v_mul_f32_e32 v25, s98, v131
	v_exp_f32_e32 v25, v25
	v_mul_f32_e32 v30, s98, v212
	v_add_f32_e32 v24, 1.0, v24
	v_rcp_f32_e32 v24, v24
	v_exp_f32_e32 v30, v30
	v_add_f32_e32 v16, 1.0, v29
	v_mul_f32_e32 v22, s98, v152
	v_mul_f32_e32 v24, v133, v24
	v_mul_f32_e32 v20, v24, v20
	v_add_f32_e32 v24, 1.0, v25
	v_mul_f32_e32 v25, s98, v132
	v_mul_f32_e32 v23, s98, v153
	v_exp_f32_e32 v25, v25
; __device__ __forceinline__ unsigned cvt_pk_bf16(float lo, float hi) { unsigned r; asm volatile("v_cvt_pk_bf16_f32 %0, %1, %2" : "=v"(r) : "v"(lo), "v"(hi)); return r; }
;     __device__ __forceinline__ void operator()(f32x4 (&acc)[2][2][4][2], const Unit& u, int ui, int wr, int wc, int fr_, int fq_) const {
;     ...
;         const int row0 = u.pm * BM + wr * 64 + fr;
; #pragma unroll
;         for (int ai = 0; ai < 2; ++ai)
; #pragma unroll
;             for (int m = 0; m < 4; ++m) { float gv[8];
; #pragma unroll
;                 for (int n = 0; n < 2; ++n)
; #pragma unroll
;                     for (int j = 0; j < 4; ++j) { const float g = acc[ai][0][m][n][j], up = acc[ai][1][m][n][j]; gv[n * 4 + j] = g * __builtin_amdgcn_rcpf(1.0f + __builtin_amdgcn_exp2f(g * -1.4426950408889634f)) * up; }
;                 u32x4 w; w.x = cvt_pk_bf16(gv[0], gv[1]); w.y = cvt_pk_bf16(gv[2], gv[3]); w.z = cvt_pk_bf16(gv[4], gv[5]); w.w = cvt_pk_bf16(gv[6], gv[7]);
;                 *(u32x4*)(G + (size_t)(row0 + ai * HALF + m * 16) * 2816 + fbase) = w; asm volatile("" ::: "memory"); }
	v_mul_f32_e32 v29, s98, v135
	v_exp_f32_e32 v22, v22
	v_exp_f32_e32 v23, v23
	v_exp_f32_e32 v29, v29
	v_add_f32_e32 v17, 1.0, v30
	v_rcp_f32_e32 v24, v24
	v_add_f32_e32 v25, 1.0, v25
	v_rcp_f32_e32 v16, v16
	v_rcp_f32_e32 v17, v17
	v_add_f32_e32 v22, 1.0, v22
	v_add_f32_e32 v23, 1.0, v23
	v_rcp_f32_e32 v25, v25
	v_add_f32_e32 v29, 1.0, v29
	v_rcp_f32_e32 v22, v22
	v_rcp_f32_e32 v23, v23
	v_rcp_f32_e32 v29, v29
	v_mul_f32_e32 v24, v131, v24
	v_mul_f32_e32 v16, v211, v16
	v_mul_f32_e32 v17, v212, v17
	v_mul_f32_e32 v18, v24, v18
	v_mul_f32_e32 v24, v132, v25
	v_mul_f32_e32 v16, v16, v104
	v_mul_f32_e32 v17, v17, v103
	v_mul_f32_e32 v22, v152, v22
	v_mul_f32_e32 v23, v153, v23
	v_mul_f32_e32 v19, v24, v19
	v_mul_f32_e32 v24, v135, v29
	v_mul_f32_e32 v22, v22, v98
	v_mul_f32_e32 v23, v23, v99
	v_mul_f32_e32 v21, v24, v21
	v_cvt_pk_bf16_f32 v16, v16, v17
	v_cvt_pk_bf16_f32 v17, v22, v23
	v_cvt_pk_bf16_f32 v18, v20, v18
	v_add_u32_e32 v20, 48, v14
	v_cvt_pk_bf16_f32 v19, v19, v21
	v_mad_i64_i32 v[20:21], s[0:1], v20, s83, v[2:3]
	v_lshl_add_u64 v[20:21], v[20:21], 0, v[4:5]
	global_store_dwordx4 v[20:21], v[16:19], off
	v_mul_f32_e32 v22, s98, v102
	v_mul_f32_e32 v21, s98, v106
	v_mul_f32_e32 v16, s98, v134
	v_mul_f32_e32 v17, s98, v130
	v_mul_f32_e32 v18, s98, v32
	v_exp_f32_e32 v16, v16
	v_exp_f32_e32 v17, v17
	v_exp_f32_e32 v18, v18
	v_mul_f32_e32 v19, s98, v33
	v_exp_f32_e32 v22, v22
	v_exp_f32_e32 v19, v19
	v_exp_f32_e32 v21, v21
	v_mul_f32_e32 v23, s98, v48
	v_exp_f32_e32 v23, v23
	v_mul_f32_e32 v24, s98, v49
	v_add_f32_e32 v16, 1.0, v16
	v_add_f32_e32 v17, 1.0, v17
	v_add_f32_e32 v18, 1.0, v18
	v_add_f32_e32 v22, 1.0, v22
	v_exp_f32_e32 v24, v24
	v_rcp_f32_e32 v16, v16
	v_rcp_f32_e32 v17, v17
	v_rcp_f32_e32 v18, v18
	v_add_f32_e32 v19, 1.0, v19
	v_add_f32_e32 v21, 1.0, v21
	v_rcp_f32_e32 v22, v22
	v_rcp_f32_e32 v19, v19
	v_rcp_f32_e32 v21, v21
	v_add_f32_e32 v23, 1.0, v23
	v_rcp_f32_e32 v23, v23
	v_add_f32_e32 v24, 1.0, v24
	v_mul_f32_e32 v16, v134, v16
	v_mul_f32_e32 v17, v130, v17
	v_mul_f32_e32 v18, v32, v18
	v_mul_f32_e32 v22, v102, v22
	v_rcp_f32_e32 v24, v24
	v_mul_f32_e32 v16, v16, v78
	v_mul_f32_e32 v17, v17, v55
	v_mul_f32_e32 v18, v18, v54
	v_mul_f32_e32 v19, v33, v19
	v_mul_f32_e32 v21, v106, v21
	v_mul_f32_e32 v22, v22, v27
	v_mul_f32_e32 v19, v19, v57
	v_mul_f32_e32 v21, v21, v26
	v_cvt_pk_bf16_f32 v16, v16, v17
	v_cvt_pk_bf16_f32 v17, v18, v19
	v_cvt_pk_bf16_f32 v18, v21, v22
	v_mul_f32_e32 v22, s98, v215
	v_add_u32_e32 v20, 0x80, v14
	v_mul_f32_e32 v23, v48, v23
	v_exp_f32_e32 v22, v22
	v_mul_f32_e32 v15, v23, v15
	v_mul_f32_e32 v23, v49, v24
	v_mad_i64_i32 v[20:21], s[0:1], v20, s83, v[2:3]
	v_mul_f32_e32 v23, v23, v28
	v_cvt_pk_bf16_f32 v19, v15, v23
	v_lshl_add_u64 v[20:21], v[20:21], 0, v[4:5]
	v_mul_f32_e32 v15, s98, v151
	v_exp_f32_e32 v15, v15
	global_store_dwordx4 v[20:21], v[16:19], off
	v_mul_f32_e32 v20, s98, v118
	v_mul_f32_e32 v21, s98, v119
	v_mul_f32_e32 v17, s98, v150
	v_mul_f32_e32 v18, s98, v155
	v_mul_f32_e32 v19, s98, v120
	v_add_f32_e32 v16, 1.0, v22
	v_exp_f32_e32 v17, v17
	v_exp_f32_e32 v18, v18
	v_exp_f32_e32 v19, v19
	v_exp_f32_e32 v20, v20
	v_exp_f32_e32 v21, v21
	v_mul_f32_e32 v22, s98, v121
	v_exp_f32_e32 v22, v22
	v_add_f32_e32 v15, 1.0, v15
	v_rcp_f32_e32 v15, v15
	v_rcp_f32_e32 v16, v16
	v_add_f32_e32 v17, 1.0, v17
	v_add_f32_e32 v18, 1.0, v18
	v_add_f32_e32 v19, 1.0, v19
	v_add_f32_e32 v20, 1.0, v20
	v_add_f32_e32 v21, 1.0, v21
	v_rcp_f32_e32 v17, v17
	v_rcp_f32_e32 v18, v18
	v_rcp_f32_e32 v19, v19
	v_rcp_f32_e32 v20, v20
	v_rcp_f32_e32 v21, v21
	v_add_f32_e32 v22, 1.0, v22
	v_rcp_f32_e32 v22, v22
	v_mul_f32_e32 v15, v151, v15
	v_mul_f32_e32 v16, v215, v16
	v_mul_f32_e32 v15, v15, v93
	v_mul_f32_e32 v16, v16, v92
	v_mul_f32_e32 v17, v150, v17
	v_mul_f32_e32 v18, v155, v18
	v_mul_f32_e32 v19, v120, v19
	v_mul_f32_e32 v20, v118, v20
	v_mul_f32_e32 v21, v119, v21
	v_mul_f32_e32 v17, v17, v90
; __device__ __forceinline__ unsigned cvt_pk_bf16(float lo, float hi) { unsigned r; asm volatile("v_cvt_pk_bf16_f32 %0, %1, %2" : "=v"(r) : "v"(lo), "v"(hi)); return r; }
;     __device__ __forceinline__ void operator()(f32x4 (&acc)[2][2][4][2], const Unit& u, int ui, int wr, int wc, int fr_, int fq_) const {
;     ...
;         const int row0 = u.pm * BM + wr * 64 + fr;
; #pragma unroll
;         for (int ai = 0; ai < 2; ++ai)
; #pragma unroll
;             for (int m = 0; m < 4; ++m) { float gv[8];
; #pragma unroll
;                 for (int n = 0; n < 2; ++n)
; #pragma unroll
;                     for (int j = 0; j < 4; ++j) { const float g = acc[ai][0][m][n][j], up = acc[ai][1][m][n][j]; gv[n * 4 + j] = g * __builtin_amdgcn_rcpf(1.0f + __builtin_amdgcn_exp2f(g * -1.4426950408889634f)) * up; }
;                 u32x4 w; w.x = cvt_pk_bf16(gv[0], gv[1]); w.y = cvt_pk_bf16(gv[2], gv[3]); w.z = cvt_pk_bf16(gv[4], gv[5]); w.w = cvt_pk_bf16(gv[6], gv[7]);
;                 *(u32x4*)(G + (size_t)(row0 + ai * HALF + m * 16) * 2816 + fbase) = w; asm volatile("" ::: "memory"); }
	v_mul_f32_e32 v18, v18, v91
	v_mul_f32_e32 v19, v19, v47
	v_mul_f32_e32 v20, v20, v46
	v_mul_f32_e32 v21, v21, v50
	v_mul_f32_e32 v22, v121, v22
	v_cvt_pk_bf16_f32 v16, v15, v16
	v_add_u32_e32 v15, 0x90, v14
	v_mul_f32_e32 v22, v22, v51
	v_cvt_pk_bf16_f32 v17, v17, v18
	v_cvt_pk_bf16_f32 v18, v19, v20
	v_cvt_pk_bf16_f32 v19, v21, v22
	v_mad_i64_i32 v[20:21], s[0:1], v15, s83, v[2:3]
	v_lshl_add_u64 v[20:21], v[20:21], 0, v[4:5]
	global_store_dwordx4 v[20:21], v[16:19], off
	v_mul_f32_e32 v20, s98, v114
	v_exp_f32_e32 v20, v20
	v_mul_f32_e32 v19, s98, v116
	v_exp_f32_e32 v19, v19
	v_mul_f32_e32 v15, s98, v147
	v_exp_f32_e32 v15, v15
	v_mul_f32_e32 v22, s98, v149
	v_add_f32_e32 v19, 1.0, v19
	v_rcp_f32_e32 v19, v19
	v_mul_f32_e32 v17, s98, v146
	v_mul_f32_e32 v21, s98, v117
	v_exp_f32_e32 v22, v22
	v_mul_f32_e32 v19, v116, v19
	v_mul_f32_e32 v19, v19, v11
	v_add_f32_e32 v11, 1.0, v20
	v_mul_f32_e32 v20, s98, v115
	v_exp_f32_e32 v20, v20
	v_exp_f32_e32 v17, v17
	v_mul_f32_e32 v18, s98, v148
	v_exp_f32_e32 v21, v21
	v_exp_f32_e32 v18, v18
	v_add_f32_e32 v15, 1.0, v15
	v_rcp_f32_e32 v11, v11
	v_add_f32_e32 v20, 1.0, v20
	v_rcp_f32_e32 v15, v15
	v_add_f32_e32 v16, 1.0, v22
	v_add_f32_e32 v17, 1.0, v17
	v_rcp_f32_e32 v20, v20
	v_add_f32_e32 v21, 1.0, v21
	v_rcp_f32_e32 v16, v16
	v_rcp_f32_e32 v17, v17
	v_add_f32_e32 v18, 1.0, v18
	v_rcp_f32_e32 v21, v21
	v_rcp_f32_e32 v18, v18
	v_mul_f32_e32 v11, v114, v11
	v_mul_f32_e32 v15, v147, v15
	v_mul_f32_e32 v22, v11, v10
	v_mul_f32_e32 v10, v115, v20
	v_mul_f32_e32 v15, v15, v89
	v_mul_f32_e32 v16, v149, v16
	v_mul_f32_e32 v17, v146, v17
	v_mul_f32_e32 v20, v10, v12
	v_mul_f32_e32 v10, v117, v21
	v_mul_f32_e32 v16, v16, v88
	v_mul_f32_e32 v17, v17, v84
	v_mul_f32_e32 v18, v148, v18
	v_mul_f32_e32 v13, v10, v13
	v_cvt_pk_bf16_f32 v10, v15, v16
	v_add_u32_e32 v15, 0xa0, v14
	v_mul_f32_e32 v18, v18, v85
	v_cvt_pk_bf16_f32 v11, v17, v18
	v_mad_i64_i32 v[16:17], s[0:1], v15, s83, v[2:3]
	v_mul_f32_e32 v15, s98, v139
	v_exp_f32_e32 v15, v15
	v_lshl_add_u64 v[16:17], v[16:17], 0, v[4:5]
	v_cvt_pk_bf16_f32 v12, v19, v22
	v_cvt_pk_bf16_f32 v13, v20, v13
	global_store_dwordx4 v[16:17], v[10:13], off
	v_mul_f32_e32 v16, s98, v110
	v_exp_f32_e32 v16, v16
	v_add_f32_e32 v10, 1.0, v15
	v_mul_f32_e32 v15, s98, v112
	v_exp_f32_e32 v15, v15
	v_mul_f32_e32 v18, s98, v141
	v_mul_f32_e32 v17, s98, v113
	v_exp_f32_e32 v18, v18
	v_add_f32_e32 v15, 1.0, v15
	v_rcp_f32_e32 v15, v15
	v_exp_f32_e32 v17, v17
	v_mul_f32_e32 v12, s98, v138
	v_mul_f32_e32 v13, s98, v140
	v_mul_f32_e32 v15, v112, v15
	v_mul_f32_e32 v15, v15, v7
	v_add_f32_e32 v7, 1.0, v16
	v_mul_f32_e32 v16, s98, v111
	v_exp_f32_e32 v16, v16
	v_exp_f32_e32 v12, v12
	v_exp_f32_e32 v13, v13
	v_rcp_f32_e32 v7, v7
	v_add_f32_e32 v16, 1.0, v16
	v_rcp_f32_e32 v10, v10
	v_add_f32_e32 v11, 1.0, v18
	v_rcp_f32_e32 v16, v16
	v_add_f32_e32 v17, 1.0, v17
	v_rcp_f32_e32 v11, v11
	v_rcp_f32_e32 v17, v17
	v_add_f32_e32 v12, 1.0, v12
	v_add_f32_e32 v13, 1.0, v13
	v_mul_f32_e32 v7, v110, v7
	v_mul_f32_e32 v10, v139, v10
	v_rcp_f32_e32 v12, v12
	v_rcp_f32_e32 v13, v13
	v_mul_f32_e32 v18, v7, v6
	v_mul_f32_e32 v6, v111, v16
	v_mul_f32_e32 v10, v10, v87
	v_mul_f32_e32 v11, v141, v11
	v_mul_f32_e32 v16, v6, v8
	v_mul_f32_e32 v6, v113, v17
	v_mul_f32_e32 v11, v11, v86
	v_mul_f32_e32 v9, v6, v9
	v_cvt_pk_bf16_f32 v6, v10, v11
	v_add_u32_e32 v10, 0xb0, v14
	v_mad_i64_i32 v[2:3], s[0:1], v10, s83, v[2:3]
	v_mul_f32_e32 v12, v138, v12
	v_mul_f32_e32 v13, v140, v13
	v_lshl_add_u64 v[2:3], v[2:3], 0, v[4:5]
	v_mul_f32_e32 v12, v12, v82
	v_mul_f32_e32 v13, v13, v83
	v_cvt_pk_bf16_f32 v7, v12, v13
	v_cvt_pk_bf16_f32 v8, v15, v18
	v_cvt_pk_bf16_f32 v9, v16, v9
	global_store_dwordx4 v[2:3], v[6:9], off
	s_andn2_b64 vcc, exec, s[6:7]
	s_mov_b64 s[0:1], -1
	s_cbranch_vccnz .LBB0_1171
	s_andn2_b64 vcc, exec, s[16:17]
	s_cbranch_vccnz .LBB0_1170
	s_barrier
	s_branch .LBB0_1170
